# xrow-loads-hoisted
# baseline (speedup 1.0000x reference)
; __global__ void __launch_bounds__(NWAVES * 64, 2) mk_fwd(Args args) {
;     ...
;         for (int m = (args.sub >= 12 ? SEQ : 4 * gw); m < SEQ; m += 4 * NGW) {
;             const f32x4* xr = (const f32x4*)(x + (size_t)m * DM) + lane;
;             f32x4 v[4][8]; float ss[4];
; #pragma unroll
;             for (int r = 0; r < 4; ++r)
; #pragma unroll
;                 for (int j = 0; j < 8; ++j) v[r][j] = __builtin_nontemporal_load(xr + 64 * j + r * (DM / 4));
; #pragma unroll
;             for (int r = 0; r < 4; ++r) { float s = 0.f;
; #pragma unroll
;                 for (int j = 0; j < 8; ++j) s += (v[r][j].x * v[r][j].x + v[r][j].y * v[r][j].y) + (v[r][j].z * v[r][j].z + v[r][j].w * v[r][j].w);
;                 ss[r] = 1.0f / sqrtf(wave_sum(s) * (1.0f / DM) + EPS); }
.LBB0_23:
	v_add_co_u32_e32 v150, vcc, 0xffff9400, v138
	s_nop 1
	v_addc_co_u32_e32 v151, vcc, -1, v139, vcc
	v_add_co_u32_e32 v152, vcc, 0xffffb400, v138
	s_nop 1
	v_addc_co_u32_e32 v153, vcc, -1, v139, vcc
	v_add_co_u32_e32 v154, vcc, 0xffffd400, v138
	s_nop 1
	v_addc_co_u32_e32 v155, vcc, -1, v139, vcc
	v_add_co_u32_e32 v156, vcc, 0xfffff400, v138
	s_nop 1
	v_addc_co_u32_e32 v157, vcc, -1, v139, vcc
	global_load_dwordx4 v[66:69], v[150:151], off offset:-4096 nt
	global_load_dwordx4 v[62:65], v[150:151], off offset:-3072 nt
	global_load_dwordx4 v[58:61], v[150:151], off offset:-2048 nt
	global_load_dwordx4 v[50:53], v[150:151], off offset:-1024 nt
	global_load_dwordx4 v[54:57], v[150:151], off nt
	global_load_dwordx4 v[46:49], v[150:151], off offset:1024 nt
	global_load_dwordx4 v[42:45], v[150:151], off offset:2048 nt
	global_load_dwordx4 v[34:37], v[150:151], off offset:3072 nt
	global_load_dwordx4 v[38:41], v[152:153], off offset:-4096 nt
	global_load_dwordx4 v[30:33], v[152:153], off offset:-3072 nt
	global_load_dwordx4 v[26:29], v[152:153], off offset:-2048 nt
	global_load_dwordx4 v[14:17], v[152:153], off offset:-1024 nt
	global_load_dwordx4 v[18:21], v[152:153], off nt
	global_load_dwordx4 v[22:25], v[152:153], off offset:1024 nt
	global_load_dwordx4 v[10:13], v[152:153], off offset:2048 nt
	global_load_dwordx4 v[6:9], v[152:153], off offset:3072 nt
	global_load_dwordx4 v[2:5], v[154:155], off offset:-4096 nt
	global_load_dwordx4 v[70:73], v[154:155], off offset:-3072 nt
	global_load_dwordx4 v[74:77], v[154:155], off offset:-2048 nt
	global_load_dwordx4 v[78:81], v[154:155], off offset:-1024 nt
	global_load_dwordx4 v[82:85], v[154:155], off nt
	global_load_dwordx4 v[86:89], v[154:155], off offset:1024 nt
	global_load_dwordx4 v[90:93], v[154:155], off offset:2048 nt
	global_load_dwordx4 v[94:97], v[154:155], off offset:3072 nt
	global_load_dwordx4 v[102:105], v[156:157], off offset:-4096 nt
	global_load_dwordx4 v[98:101], v[156:157], off offset:-3072 nt
	global_load_dwordx4 v[110:113], v[156:157], off offset:-2048 nt
	global_load_dwordx4 v[106:109], v[156:157], off offset:-1024 nt
	global_load_dwordx4 v[118:121], v[156:157], off nt
	global_load_dwordx4 v[114:117], v[156:157], off offset:1024 nt
	global_load_dwordx4 v[126:129], v[156:157], off offset:2048 nt
	global_load_dwordx4 v[122:125], v[156:157], off offset:3072 nt
	s_waitcnt vmcnt(24)
	v_mul_f32_e32 v160, v67, v67
	v_mul_f32_e32 v171, v69, v69
	v_fmac_f32_e32 v160, v66, v66
	v_fmac_f32_e32 v171, v68, v68
	v_add_f32_e32 v160, v160, v171
	v_mul_f32_e32 v172, v63, v63
	v_mul_f32_e32 v173, v65, v65
	v_fmac_f32_e32 v172, v62, v62
	v_fmac_f32_e32 v173, v64, v64
	v_add_f32_e32 v172, v172, v173
	v_add_f32_e32 v160, v160, v172
	v_mul_f32_e32 v174, v59, v59
	v_mul_f32_e32 v175, v61, v61
	v_fmac_f32_e32 v174, v58, v58
	v_fmac_f32_e32 v175, v60, v60
	v_add_f32_e32 v174, v174, v175
	v_add_f32_e32 v160, v160, v174
	v_mul_f32_e32 v176, v51, v51
	v_mul_f32_e32 v177, v53, v53
	v_fmac_f32_e32 v176, v50, v50
	v_fmac_f32_e32 v177, v52, v52
	v_add_f32_e32 v176, v176, v177
	v_add_f32_e32 v160, v160, v176
	v_mul_f32_e32 v178, v55, v55
	v_mul_f32_e32 v179, v57, v57
	v_fmac_f32_e32 v178, v54, v54
	v_fmac_f32_e32 v179, v56, v56
	v_add_f32_e32 v178, v178, v179
	v_add_f32_e32 v160, v160, v178
	v_mul_f32_e32 v180, v47, v47
	v_mul_f32_e32 v181, v49, v49
	v_fmac_f32_e32 v180, v46, v46
	v_fmac_f32_e32 v181, v48, v48
	v_add_f32_e32 v180, v180, v181
	v_add_f32_e32 v160, v160, v180
	v_mul_f32_e32 v182, v43, v43
	v_mul_f32_e32 v183, v45, v45
	v_fmac_f32_e32 v182, v42, v42
	v_fmac_f32_e32 v183, v44, v44
	v_add_f32_e32 v182, v182, v183
	v_add_f32_e32 v160, v160, v182
	v_mul_f32_e32 v184, v35, v35
	v_mul_f32_e32 v185, v37, v37
	v_fmac_f32_e32 v184, v34, v34
	v_fmac_f32_e32 v185, v36, v36
	v_add_f32_e32 v184, v184, v185
	v_add_f32_e32 v160, v160, v184
	s_waitcnt vmcnt(16)
	v_mul_f32_e32 v161, v39, v39
	v_mul_f32_e32 v171, v41, v41
	v_fmac_f32_e32 v161, v38, v38
	v_fmac_f32_e32 v171, v40, v40
	v_add_f32_e32 v161, v161, v171
	v_mul_f32_e32 v172, v31, v31
	v_mul_f32_e32 v173, v33, v33
	v_fmac_f32_e32 v172, v30, v30
	v_fmac_f32_e32 v173, v32, v32
	v_add_f32_e32 v172, v172, v173
	v_add_f32_e32 v161, v161, v172
	v_mul_f32_e32 v174, v27, v27
	v_mul_f32_e32 v175, v29, v29
	v_fmac_f32_e32 v174, v26, v26
	v_fmac_f32_e32 v175, v28, v28
	v_add_f32_e32 v174, v174, v175
	v_add_f32_e32 v161, v161, v174
	v_mul_f32_e32 v176, v15, v15
	v_mul_f32_e32 v177, v17, v17
	v_fmac_f32_e32 v176, v14, v14
	v_fmac_f32_e32 v177, v16, v16
	v_add_f32_e32 v176, v176, v177
	v_add_f32_e32 v161, v161, v176
	v_mul_f32_e32 v178, v19, v19
	v_mul_f32_e32 v179, v21, v21
	v_fmac_f32_e32 v178, v18, v18
	v_fmac_f32_e32 v179, v20, v20
	v_add_f32_e32 v178, v178, v179
	v_add_f32_e32 v161, v161, v178
	v_mul_f32_e32 v180, v23, v23
	v_mul_f32_e32 v181, v25, v25
	v_fmac_f32_e32 v180, v22, v22
	v_fmac_f32_e32 v181, v24, v24
	v_add_f32_e32 v180, v180, v181
	v_add_f32_e32 v161, v161, v180
	v_mul_f32_e32 v182, v11, v11
	v_mul_f32_e32 v183, v13, v13
	v_fmac_f32_e32 v182, v10, v10
	v_fmac_f32_e32 v183, v12, v12
	v_add_f32_e32 v182, v182, v183
	v_add_f32_e32 v161, v161, v182
	v_mul_f32_e32 v184, v7, v7
	v_mul_f32_e32 v185, v9, v9
	v_fmac_f32_e32 v184, v6, v6
	v_fmac_f32_e32 v185, v8, v8
	v_add_f32_e32 v184, v184, v185
	v_add_f32_e32 v161, v161, v184
	s_waitcnt vmcnt(8)
; __device__ __forceinline__ float wave_sum(float v) {
; #pragma unroll
;     for (int o = 1; o < 64; o <<= 1) v += __shfl_xor(v, o);
;     return v;
; }
; __global__ void __launch_bounds__(NWAVES * 64, 2) mk_fwd(Args args) {
;     ...
;             for (int r = 0; r < 4; ++r) { float s = 0.f;
; #pragma unroll
;                 for (int j = 0; j < 8; ++j) s += (v[r][j].x * v[r][j].x + v[r][j].y * v[r][j].y) + (v[r][j].z * v[r][j].z + v[r][j].w * v[r][j].w);
;                 ss[r] = 1.0f / sqrtf(wave_sum(s) * (1.0f / DM) + EPS); }
	v_mul_f32_e32 v162, v3, v3
	v_mul_f32_e32 v171, v5, v5
	v_fmac_f32_e32 v162, v2, v2
	v_fmac_f32_e32 v171, v4, v4
	v_add_f32_e32 v162, v162, v171
	v_mul_f32_e32 v172, v71, v71
	v_mul_f32_e32 v173, v73, v73
	v_fmac_f32_e32 v172, v70, v70
	v_fmac_f32_e32 v173, v72, v72
	v_add_f32_e32 v172, v172, v173
	v_add_f32_e32 v162, v162, v172
	v_mul_f32_e32 v174, v75, v75
	v_mul_f32_e32 v175, v77, v77
	v_fmac_f32_e32 v174, v74, v74
	v_fmac_f32_e32 v175, v76, v76
	v_add_f32_e32 v174, v174, v175
	v_add_f32_e32 v162, v162, v174
	v_mul_f32_e32 v176, v79, v79
	v_mul_f32_e32 v177, v81, v81
	v_fmac_f32_e32 v176, v78, v78
	v_fmac_f32_e32 v177, v80, v80
	v_add_f32_e32 v176, v176, v177
	v_add_f32_e32 v162, v162, v176
	v_mul_f32_e32 v178, v83, v83
	v_mul_f32_e32 v179, v85, v85
	v_fmac_f32_e32 v178, v82, v82
	v_fmac_f32_e32 v179, v84, v84
	v_add_f32_e32 v178, v178, v179
	v_add_f32_e32 v162, v162, v178
	v_mul_f32_e32 v180, v87, v87
	v_mul_f32_e32 v181, v89, v89
	v_fmac_f32_e32 v180, v86, v86
	v_fmac_f32_e32 v181, v88, v88
	v_add_f32_e32 v180, v180, v181
	v_add_f32_e32 v162, v162, v180
	v_mul_f32_e32 v182, v91, v91
	v_mul_f32_e32 v183, v93, v93
	v_fmac_f32_e32 v182, v90, v90
	v_fmac_f32_e32 v183, v92, v92
	v_add_f32_e32 v182, v182, v183
	v_add_f32_e32 v162, v162, v182
	v_mul_f32_e32 v184, v95, v95
	v_mul_f32_e32 v185, v97, v97
	v_fmac_f32_e32 v184, v94, v94
	v_fmac_f32_e32 v185, v96, v96
	v_add_f32_e32 v184, v184, v185
	v_add_f32_e32 v162, v162, v184
	s_waitcnt vmcnt(0)
	v_mul_f32_e32 v163, v103, v103
	v_mul_f32_e32 v171, v105, v105
	v_fmac_f32_e32 v163, v102, v102
	v_fmac_f32_e32 v171, v104, v104
	v_add_f32_e32 v163, v163, v171
	v_mul_f32_e32 v172, v99, v99
	v_mul_f32_e32 v173, v101, v101
	v_fmac_f32_e32 v172, v98, v98
	v_fmac_f32_e32 v173, v100, v100
	v_add_f32_e32 v172, v172, v173
	v_add_f32_e32 v163, v163, v172
	v_mul_f32_e32 v174, v111, v111
	v_mul_f32_e32 v175, v113, v113
	v_fmac_f32_e32 v174, v110, v110
	v_fmac_f32_e32 v175, v112, v112
	v_add_f32_e32 v174, v174, v175
	v_add_f32_e32 v163, v163, v174
	v_mul_f32_e32 v176, v107, v107
	v_mul_f32_e32 v177, v109, v109
	v_fmac_f32_e32 v176, v106, v106
	v_fmac_f32_e32 v177, v108, v108
	v_add_f32_e32 v176, v176, v177
	v_add_f32_e32 v163, v163, v176
	v_mul_f32_e32 v178, v119, v119
	v_mul_f32_e32 v179, v121, v121
	v_fmac_f32_e32 v178, v118, v118
	v_fmac_f32_e32 v179, v120, v120
	v_add_f32_e32 v178, v178, v179
	v_add_f32_e32 v163, v163, v178
	v_mul_f32_e32 v180, v115, v115
	v_mul_f32_e32 v181, v117, v117
	v_fmac_f32_e32 v180, v114, v114
	v_fmac_f32_e32 v181, v116, v116
	v_add_f32_e32 v180, v180, v181
	v_add_f32_e32 v163, v163, v180
	v_mul_f32_e32 v182, v127, v127
	v_mul_f32_e32 v183, v129, v129
	v_fmac_f32_e32 v182, v126, v126
	v_fmac_f32_e32 v183, v128, v128
	v_add_f32_e32 v182, v182, v183
	v_add_f32_e32 v163, v163, v182
	v_mul_f32_e32 v184, v123, v123
	v_mul_f32_e32 v185, v125, v125
	v_fmac_f32_e32 v184, v122, v122
	v_fmac_f32_e32 v185, v124, v124
	v_add_f32_e32 v184, v184, v185
	v_add_f32_e32 v163, v163, v184
	ds_bpermute_b32 v164, v1, v160
	ds_bpermute_b32 v165, v1, v161
	ds_bpermute_b32 v166, v1, v162
	ds_bpermute_b32 v167, v1, v163
	s_waitcnt lgkmcnt(0)
	v_add_f32_e32 v160, v160, v164
	v_add_f32_e32 v161, v161, v165
	v_add_f32_e32 v162, v162, v166
	v_add_f32_e32 v163, v163, v167
	ds_bpermute_b32 v164, v141, v160
	ds_bpermute_b32 v165, v141, v161
	ds_bpermute_b32 v166, v141, v162
	ds_bpermute_b32 v167, v141, v163
	s_waitcnt lgkmcnt(0)
	v_add_f32_e32 v160, v160, v164
	v_add_f32_e32 v161, v161, v165
	v_add_f32_e32 v162, v162, v166
	v_add_f32_e32 v163, v163, v167
	ds_bpermute_b32 v164, v142, v160
	ds_bpermute_b32 v165, v142, v161
	ds_bpermute_b32 v166, v142, v162
	ds_bpermute_b32 v167, v142, v163
	s_waitcnt lgkmcnt(0)
	v_add_f32_e32 v160, v160, v164
	v_add_f32_e32 v161, v161, v165
	v_add_f32_e32 v162, v162, v166
	v_add_f32_e32 v163, v163, v167
	ds_bpermute_b32 v164, v143, v160
	ds_bpermute_b32 v165, v143, v161
	ds_bpermute_b32 v166, v143, v162
	ds_bpermute_b32 v167, v143, v163
	s_waitcnt lgkmcnt(0)
	v_add_f32_e32 v160, v160, v164
	v_add_f32_e32 v161, v161, v165
	v_add_f32_e32 v162, v162, v166
	v_add_f32_e32 v163, v163, v167
	ds_bpermute_b32 v164, v144, v160
	ds_bpermute_b32 v165, v144, v161
	ds_bpermute_b32 v166, v144, v162
	ds_bpermute_b32 v167, v144, v163
	s_waitcnt lgkmcnt(0)
	v_add_f32_e32 v160, v160, v164
	v_add_f32_e32 v161, v161, v165
	v_add_f32_e32 v162, v162, v166
	v_add_f32_e32 v163, v163, v167
	ds_bpermute_b32 v164, v145, v160
	ds_bpermute_b32 v165, v145, v161
	ds_bpermute_b32 v166, v145, v162
	ds_bpermute_b32 v167, v145, v163
	s_waitcnt lgkmcnt(0)
; __global__ void __launch_bounds__(NWAVES * 64, 2) mk_fwd(Args args) {
;     ...
;                 ss[r] = 1.0f / sqrtf(wave_sum(s) * (1.0f / DM) + EPS); }
;             if (lane == 0) *(f32x4*)((float*)(ws + WS_R0) + m) = (f32x4){ss[0], ss[1], ss[2], ss[3]};
	v_add_f32_e32 v160, v160, v164
	v_add_f32_e32 v161, v161, v165
	v_add_f32_e32 v162, v162, v166
	v_add_f32_e32 v163, v163, v167
	v_fmamk_f32 v186, v160, 0x3a000000, v146
	v_mul_f32_e32 v187, 0x4f800000, v186
	v_cmp_gt_f32_e64 s[4:5], s13, v186
	s_nop 1
	v_cndmask_b32_e64 v188, v186, v187, s[4:5]
	v_sqrt_f32_e32 v189, v188
	s_nop 0
	v_add_u32_e32 v190, -1, v189
	v_fma_f32 v191, -v190, v189, v188
	v_add_u32_e32 v192, 1, v189
	v_cmp_ge_f32_e32 vcc, 0, v191
	v_fma_f32 v193, -v192, v189, v188
	s_nop 0
	v_cndmask_b32_e32 v195, v189, v190, vcc
	v_cmp_lt_f32_e32 vcc, 0, v193
	s_nop 1
	v_cndmask_b32_e32 v195, v195, v192, vcc
	v_mul_f32_e32 v196, 0x37800000, v195
	v_cndmask_b32_e64 v195, v195, v196, s[4:5]
	v_cmp_class_f32_e32 vcc, v188, v147
	s_nop 1
	v_cndmask_b32_e32 v197, v195, v188, vcc
	v_div_scale_f32 v198, s[4:5], v197, v197, 1.0
	v_rcp_f32_e32 v199, v198
	v_div_scale_f32 v200, vcc, 1.0, v197, 1.0
	v_fma_f32 v201, -v198, v199, 1.0
	v_fmac_f32_e32 v199, v201, v199
	v_mul_f32_e32 v202, v200, v199
	v_fma_f32 v203, -v198, v202, v200
	v_fmac_f32_e32 v202, v203, v199
	v_fma_f32 v204, -v198, v202, v200
	v_div_fmas_f32 v205, v204, v199, v202
	v_div_fixup_f32 v130, v205, v197, 1.0
	v_fmamk_f32 v186, v161, 0x3a000000, v146
	v_mul_f32_e32 v187, 0x4f800000, v186
	v_cmp_gt_f32_e64 s[4:5], s13, v186
	s_nop 1
	v_cndmask_b32_e64 v188, v186, v187, s[4:5]
	v_sqrt_f32_e32 v189, v188
	s_nop 0
	v_add_u32_e32 v190, -1, v189
	v_fma_f32 v191, -v190, v189, v188
	v_add_u32_e32 v192, 1, v189
	v_cmp_ge_f32_e32 vcc, 0, v191
	v_fma_f32 v193, -v192, v189, v188
	s_nop 0
	v_cndmask_b32_e32 v195, v189, v190, vcc
	v_cmp_lt_f32_e32 vcc, 0, v193
	s_nop 1
	v_cndmask_b32_e32 v195, v195, v192, vcc
	v_mul_f32_e32 v196, 0x37800000, v195
	v_cndmask_b32_e64 v195, v195, v196, s[4:5]
	v_cmp_class_f32_e32 vcc, v188, v147
	s_nop 1
	v_cndmask_b32_e32 v197, v195, v188, vcc
	v_div_scale_f32 v198, s[4:5], v197, v197, 1.0
	v_rcp_f32_e32 v199, v198
	v_div_scale_f32 v200, vcc, 1.0, v197, 1.0
	v_fma_f32 v201, -v198, v199, 1.0
	v_fmac_f32_e32 v199, v201, v199
	v_mul_f32_e32 v202, v200, v199
	v_fma_f32 v203, -v198, v202, v200
	v_fmac_f32_e32 v202, v203, v199
	v_fma_f32 v204, -v198, v202, v200
	v_div_fmas_f32 v205, v204, v199, v202
	v_div_fixup_f32 v140, v205, v197, 1.0
	v_fmamk_f32 v186, v162, 0x3a000000, v146
	v_mul_f32_e32 v187, 0x4f800000, v186
	v_cmp_gt_f32_e64 s[4:5], s13, v186
	s_nop 1
	v_cndmask_b32_e64 v188, v186, v187, s[4:5]
	v_sqrt_f32_e32 v189, v188
	s_nop 0
	v_add_u32_e32 v190, -1, v189
	v_fma_f32 v191, -v190, v189, v188
	v_add_u32_e32 v192, 1, v189
	v_cmp_ge_f32_e32 vcc, 0, v191
	v_fma_f32 v193, -v192, v189, v188
	s_nop 0
	v_cndmask_b32_e32 v195, v189, v190, vcc
	v_cmp_lt_f32_e32 vcc, 0, v193
	s_nop 1
	v_cndmask_b32_e32 v195, v195, v192, vcc
	v_mul_f32_e32 v196, 0x37800000, v195
	v_cndmask_b32_e64 v195, v195, v196, s[4:5]
	v_cmp_class_f32_e32 vcc, v188, v147
	s_nop 1
	v_cndmask_b32_e32 v197, v195, v188, vcc
	v_div_scale_f32 v198, s[4:5], v197, v197, 1.0
	v_rcp_f32_e32 v199, v198
	v_div_scale_f32 v200, vcc, 1.0, v197, 1.0
	v_fma_f32 v201, -v198, v199, 1.0
	v_fmac_f32_e32 v199, v201, v199
	v_mul_f32_e32 v202, v200, v199
	v_fma_f32 v203, -v198, v202, v200
	v_fmac_f32_e32 v202, v203, v199
	v_fma_f32 v204, -v198, v202, v200
	v_div_fmas_f32 v205, v204, v199, v202
	v_div_fixup_f32 v132, v205, v197, 1.0
	v_fmamk_f32 v186, v163, 0x3a000000, v146
	v_mul_f32_e32 v187, 0x4f800000, v186
	v_cmp_gt_f32_e64 s[4:5], s13, v186
	s_nop 1
	v_cndmask_b32_e64 v188, v186, v187, s[4:5]
	v_sqrt_f32_e32 v189, v188
	s_nop 0
	v_add_u32_e32 v190, -1, v189
	v_fma_f32 v191, -v190, v189, v188
	v_add_u32_e32 v192, 1, v189
	v_cmp_ge_f32_e32 vcc, 0, v191
	v_fma_f32 v193, -v192, v189, v188
	s_nop 0
	v_cndmask_b32_e32 v195, v189, v190, vcc
	v_cmp_lt_f32_e32 vcc, 0, v193
	s_nop 1
	v_cndmask_b32_e32 v195, v195, v192, vcc
	v_mul_f32_e32 v196, 0x37800000, v195
	v_cndmask_b32_e64 v195, v195, v196, s[4:5]
	v_cmp_class_f32_e32 vcc, v188, v147
	s_nop 1
	v_cndmask_b32_e32 v197, v195, v188, vcc
	v_div_scale_f32 v198, s[4:5], v197, v197, 1.0
	v_rcp_f32_e32 v199, v198
	v_div_scale_f32 v200, vcc, 1.0, v197, 1.0
	v_fma_f32 v201, -v198, v199, 1.0
	v_fmac_f32_e32 v199, v201, v199
	v_mul_f32_e32 v202, v200, v199
	v_fma_f32 v203, -v198, v202, v200
	v_fmac_f32_e32 v202, v203, v199
	v_fma_f32 v204, -v198, v202, v200
	v_div_fmas_f32 v205, v204, v199, v202
	v_div_fixup_f32 v136, v205, v197, 1.0
	s_and_saveexec_b64 s[4:5], s[2:3]
	s_cbranch_execz .LBB0_22
	s_add_u32 s6, s54, s58
	s_addc_u32 s7, s55, s59
	v_mov_b32_e32 v131, v140
	v_mov_b32_e32 v133, v136
	global_store_dwordx4 v137, v[130:133], s[6:7]
	s_branch .LBB0_22
